# combined latency polish: k-mean sums, phase-start tables, deferred row-scale table, unit-loop head waits moved to preheaders
# speedup vs baseline: 1.0013x; 1.0013x over previous
; #define LAS __attribute__((address_space(3)))
; __device__ __forceinline__ float bflo(unsigned u) { return __uint_as_float(u << 16); }
; __device__ __forceinline__ float bfhi(unsigned u) { return __uint_as_float(u & 0xffff0000u); }
; __device__ __forceinline__ float sigm(float x) { return frcp(1.f + fexp(-x)); }
; __device__ __forceinline__ void hgrn_stepA(const Args& a, int l, LAS unsigned char* lds, int tid, int hh, const HIn& in, float (&kf)[16]) {
;     LAS float* LF = (LAS float*)lds;
;     LAS float* PT = (LAS float*)(lds + 32768);
; #pragma unroll
;     for (int ii = 0; ii < 2; ++ii) {
;         const int cid = tid + 512 * ii, t = cid >> 4, d0 = (cid & 15) * 8;
;         const u32x4 u = in.f[ii];
;         float fl[8] = {bflo(u.x), bfhi(u.x), bflo(u.y), bfhi(u.y), bflo(u.z), bfhi(u.z), bflo(u.w), bfhi(u.w)};
;         float lf[8];
;         const LAS float* LB = (const LAS float*)(lds + 106496) + hh * 128 + d0; const f32x4 lb0 = *(const LAS f32x4*)LB, lb1 = *(const LAS f32x4*)(LB + 4);
;         const float lbv[8] = {lb0.x, lb0.y, lb0.z, lb0.w, lb1.x, lb1.y, lb1.z, lb1.w};
; #pragma unroll
;         for (int i = 0; i < 8; ++i) { const float lb = lbv[i]; const float sg = sigm(fl[i]);
;             const float f = lb + (1.f - lb) * sg; lf[i] = __logf(f); kf[ii * 8 + i] = (1.f - lb) * (1.f - sg); }
;         *(LAS f32x4*)(LF + t * 128 + d0) = (f32x4){lf[0], lf[1], lf[2], lf[3]}; *(LAS f32x4*)(LF + t * 128 + d0 + 4) = (f32x4){lf[4], lf[5], lf[6], lf[7]};
;     }
; }
.LBB0_438:
	s_mov_b32 s4, s98
	s_add_i32 s4, s8, s4
	s_cmp_ge_i32 s4, s99
	v_lshlrev_b32_e32 v21, 16, v12
	s_cselect_b64 s[52:53], -1, 0
	s_cmp_lt_i32 s4, s99
	v_mul_f32_e32 v21, 0xbfb8aa3b, v21
	s_cselect_b32 s6, s4, s8
	s_ashr_i32 s40, s8, 5
	v_exp_f32_e32 v21, v21
	s_lshl_b32 s9, s40, 9
	s_and_b32 s9, s9, 0x600
	v_add_u32_e32 v20, s9, v64
	v_and_b32_e32 v22, 0xffff0000, v12
	v_lshlrev_b32_e32 v23, 16, v13
	v_and_b32_e32 v28, 0xffff0000, v13
	v_lshlrev_b32_e32 v37, 16, v14
	v_and_b32_e32 v38, 0xffff0000, v14
	v_lshlrev_b32_e32 v42, 16, v15
	v_and_b32_e32 v43, 0xffff0000, v15
	ds_read_b128 v[16:19], v20
	ds_read_b128 v[12:15], v20 offset:16
	v_add_f32_e32 v21, 1.0, v21
	v_rcp_f32_e32 v26, v21
	v_mul_f32_e32 v21, 0xbfb8aa3b, v22
	v_exp_f32_e32 v21, v21
	s_waitcnt lgkmcnt(1)
	v_pk_add_f32 v[24:25], v[16:17], 1.0 op_sel_hi:[1,0] neg_lo:[1,0] neg_hi:[1,0]
	v_and_b32_e32 v22, 0xffff0000, v10
	v_fma_f32 v16, v26, v24, v16
	v_add_f32_e32 v21, 1.0, v21
	v_cmp_gt_f32_e32 vcc, s28, v16
	v_rcp_f32_e32 v27, v21
	s_ashr_i32 s10, s6, 7
	v_cndmask_b32_e64 v21, 0, 32, vcc
	v_ldexp_f32 v16, v16, v21
	v_log_f32_e32 v16, v16
	v_fma_f32 v17, v27, v25, v17
	s_ashr_i32 s11, s10, 31
	s_lshl_b32 s9, s6, 6
	v_mul_f32_e32 v21, 0x3f317217, v16
	v_fma_f32 v21, v16, s29, -v21
	v_fmac_f32_e32 v21, 0x3377d1cf, v16
	v_fmac_f32_e32 v21, 0x3f317217, v16
	v_cmp_lt_f32_e64 s[50:51], |v16|, s30
	s_lshl_b64 s[10:11], s[10:11], 11
	s_and_b32 s9, s9, 0x7c0
	v_cndmask_b32_e64 v16, v16, v21, s[50:51]
	v_cndmask_b32_e32 v21, 0, v190, vcc
	v_cmp_gt_f32_e32 vcc, s28, v17
	v_sub_f32_e32 v16, v16, v21
	s_or_b32 s10, s10, s9
	v_cndmask_b32_e64 v21, 0, 32, vcc
	v_ldexp_f32 v17, v17, v21
	v_log_f32_e32 v17, v17
	s_lshl_b32 s6, s6, 3
	s_and_b32 s6, s6, 0x300
	v_readfirstlane_b32 s5, v96
	v_mul_f32_e32 v21, 0x3f317217, v17
	v_fma_f32 v21, v17, s29, -v21
	v_fmac_f32_e32 v21, 0x3377d1cf, v17
	v_fmac_f32_e32 v21, 0x3f317217, v17
	v_cmp_lt_f32_e64 s[50:51], |v17|, s30
	v_mov_b32_e32 v93, 0
	s_nop 0
	v_cndmask_b32_e64 v17, v17, v21, s[50:51]
	v_cndmask_b32_e32 v21, 0, v190, vcc
	v_sub_f32_e32 v17, v17, v21
	v_mul_f32_e32 v21, 0xbfb8aa3b, v23
	v_exp_f32_e32 v21, v21
	v_lshlrev_b32_e32 v23, 16, v11
	v_add_f32_e32 v21, 1.0, v21
	v_rcp_f32_e32 v30, v21
	v_mul_f32_e32 v21, 0xbfb8aa3b, v28
	v_exp_f32_e32 v21, v21
	v_pk_add_f32 v[28:29], v[18:19], 1.0 op_sel_hi:[1,0] neg_lo:[1,0] neg_hi:[1,0]
	v_add_f32_e32 v21, 1.0, v21
	v_fma_f32 v18, v30, v28, v18
	v_cmp_gt_f32_e32 vcc, s28, v18
	v_rcp_f32_e32 v31, v21
	s_nop 0
	v_cndmask_b32_e64 v21, 0, 32, vcc
	v_ldexp_f32 v18, v18, v21
	v_log_f32_e32 v18, v18
	v_fmac_f32_e32 v19, v31, v29
	v_mul_f32_e32 v21, 0x3f317217, v18
	v_fma_f32 v21, v18, s29, -v21
	v_fmac_f32_e32 v21, 0x3377d1cf, v18
	v_fmac_f32_e32 v21, 0x3f317217, v18
	v_cmp_lt_f32_e64 s[50:51], |v18|, s30
	s_nop 1
	v_cndmask_b32_e64 v18, v18, v21, s[50:51]
	v_cndmask_b32_e32 v21, 0, v190, vcc
	v_cmp_gt_f32_e32 vcc, s28, v19
	v_sub_f32_e32 v18, v18, v21
	s_nop 0
	v_cndmask_b32_e64 v21, 0, 32, vcc
	v_ldexp_f32 v19, v19, v21
	v_log_f32_e32 v19, v19
	s_nop 0
	v_mul_f32_e32 v21, 0x3f317217, v19
	v_fma_f32 v21, v19, s29, -v21
	v_fmac_f32_e32 v21, 0x3377d1cf, v19
	v_fmac_f32_e32 v21, 0x3f317217, v19
	v_cmp_lt_f32_e64 s[50:51], |v19|, s30
	s_nop 1
	v_cndmask_b32_e64 v19, v19, v21, s[50:51]
	v_cndmask_b32_e32 v21, 0, v190, vcc
	v_sub_f32_e32 v19, v19, v21
	v_mul_f32_e32 v21, 0xbfb8aa3b, v37
	v_exp_f32_e32 v21, v21
	v_and_b32_e32 v37, 0xffff0000, v11
	v_add_f32_e32 v21, 1.0, v21
	v_rcp_f32_e32 v40, v21
	v_mul_f32_e32 v21, 0xbfb8aa3b, v38
	v_exp_f32_e32 v21, v21
	s_waitcnt lgkmcnt(0)
	v_pk_add_f32 v[38:39], v[12:13], 1.0 op_sel_hi:[1,0] neg_lo:[1,0] neg_hi:[1,0]
	v_add_f32_e32 v21, 1.0, v21
	v_fma_f32 v12, v40, v38, v12
	v_cmp_gt_f32_e32 vcc, s28, v12
	v_rcp_f32_e32 v41, v21
	s_nop 0
	v_cndmask_b32_e64 v21, 0, 32, vcc
	v_ldexp_f32 v12, v12, v21
	v_log_f32_e32 v12, v12
	v_fma_f32 v13, v41, v39, v13
	v_mul_f32_e32 v21, 0x3f317217, v12
	v_fma_f32 v21, v12, s29, -v21
	v_fmac_f32_e32 v21, 0x3377d1cf, v12
	v_fmac_f32_e32 v21, 0x3f317217, v12
	v_cmp_lt_f32_e64 s[50:51], |v12|, s30
	s_nop 1
	v_cndmask_b32_e64 v12, v12, v21, s[50:51]
	v_cndmask_b32_e32 v21, 0, v190, vcc
	v_cmp_gt_f32_e32 vcc, s28, v13
	v_sub_f32_e32 v12, v12, v21
	s_nop 0
	v_cndmask_b32_e64 v21, 0, 32, vcc
	v_ldexp_f32 v13, v13, v21
	v_log_f32_e32 v13, v13
	s_nop 0
	v_mul_f32_e32 v21, 0x3f317217, v13
	v_fma_f32 v21, v13, s29, -v21
	v_fmac_f32_e32 v21, 0x3377d1cf, v13
	v_fmac_f32_e32 v21, 0x3f317217, v13
	v_cmp_lt_f32_e64 s[50:51], |v13|, s30
	s_nop 1
	v_cndmask_b32_e64 v13, v13, v21, s[50:51]
	v_cndmask_b32_e32 v21, 0, v190, vcc
	v_sub_f32_e32 v13, v13, v21
	v_mul_f32_e32 v21, 0xbfb8aa3b, v42
	v_exp_f32_e32 v21, v21
	s_nop 0
	v_add_f32_e32 v21, 1.0, v21
	v_rcp_f32_e32 v46, v21
	v_mul_f32_e32 v21, 0xbfb8aa3b, v43
	v_exp_f32_e32 v21, v21
	v_pk_add_f32 v[42:43], v[14:15], 1.0 op_sel_hi:[1,0] neg_lo:[1,0] neg_hi:[1,0]
	v_add_f32_e32 v21, 1.0, v21
	v_fma_f32 v14, v46, v42, v14
	v_cmp_gt_f32_e32 vcc, s28, v14
	v_rcp_f32_e32 v47, v21
	s_nop 0
	v_cndmask_b32_e64 v21, 0, 32, vcc
	v_ldexp_f32 v14, v14, v21
	v_log_f32_e32 v14, v14
	v_fmac_f32_e32 v15, v47, v43
	v_mul_f32_e32 v21, 0x3f317217, v14
	v_fma_f32 v21, v14, s29, -v21
	v_fmac_f32_e32 v21, 0x3377d1cf, v14
	v_fmac_f32_e32 v21, 0x3f317217, v14
	v_cmp_lt_f32_e64 s[50:51], |v14|, s30
	s_nop 1
	v_cndmask_b32_e64 v14, v14, v21, s[50:51]
	v_cndmask_b32_e32 v21, 0, v190, vcc
	v_cmp_gt_f32_e32 vcc, s28, v15
	v_sub_f32_e32 v14, v14, v21
	s_nop 0
	v_cndmask_b32_e64 v21, 0, 32, vcc
	v_ldexp_f32 v15, v15, v21
	v_log_f32_e32 v15, v15
	s_nop 0
	v_mul_f32_e32 v21, 0x3f317217, v15
	v_fma_f32 v21, v15, s29, -v21
	v_fmac_f32_e32 v21, 0x3377d1cf, v15
	v_fmac_f32_e32 v21, 0x3f317217, v15
	v_cmp_lt_f32_e64 s[50:51], |v15|, s30
	s_nop 1
	v_cndmask_b32_e64 v15, v15, v21, s[50:51]
	v_cndmask_b32_e32 v21, 0, v190, vcc
	v_sub_f32_e32 v15, v15, v21
	ds_write_b128 v66, v[16:19]
	ds_write_b128 v66, v[12:15] offset:16
	v_lshlrev_b32_e32 v16, 16, v8
	v_mul_f32_e32 v16, 0xbfb8aa3b, v16
	v_exp_f32_e32 v16, v16
	v_and_b32_e32 v17, 0xffff0000, v8
	v_lshlrev_b32_e32 v18, 16, v9
	v_and_b32_e32 v19, 0xffff0000, v9
	v_lshlrev_b32_e32 v21, 16, v10
	ds_read_b128 v[12:15], v20
	ds_read_b128 v[8:11], v20 offset:16
	v_add_f32_e32 v16, 1.0, v16
	v_rcp_f32_e32 v50, v16
	v_mul_f32_e32 v16, 0xbfb8aa3b, v17
	v_exp_f32_e32 v16, v16
	s_waitcnt lgkmcnt(1)
; #define LAS __attribute__((address_space(3)))
; __device__ __forceinline__ float bflo(unsigned u) { return __uint_as_float(u << 16); }
; __device__ __forceinline__ float bfhi(unsigned u) { return __uint_as_float(u & 0xffff0000u); }
; __device__ __forceinline__ float sigm(float x) { return frcp(1.f + fexp(-x)); }
; #define BAR_LDS() do { asm volatile("s_waitcnt lgkmcnt(0)" ::: "memory"); __builtin_amdgcn_s_barrier(); asm volatile("" ::: "memory"); } while (0)
; __device__ __forceinline__ void hgrn_stepA(const Args& a, int l, LAS unsigned char* lds, int tid, int hh, const HIn& in, float (&kf)[16]) {
;     LAS float* LF = (LAS float*)lds;
;     LAS float* PT = (LAS float*)(lds + 32768);
; #pragma unroll
;     for (int ii = 0; ii < 2; ++ii) {
;         const int cid = tid + 512 * ii, t = cid >> 4, d0 = (cid & 15) * 8;
;         const u32x4 u = in.f[ii];
;         float fl[8] = {bflo(u.x), bfhi(u.x), bflo(u.y), bfhi(u.y), bflo(u.z), bfhi(u.z), bflo(u.w), bfhi(u.w)};
;         float lf[8];
;         const LAS float* LB = (const LAS float*)(lds + 106496) + hh * 128 + d0; const f32x4 lb0 = *(const LAS f32x4*)LB, lb1 = *(const LAS f32x4*)(LB + 4);
;         const float lbv[8] = {lb0.x, lb0.y, lb0.z, lb0.w, lb1.x, lb1.y, lb1.z, lb1.w};
; #pragma unroll
;         for (int i = 0; i < 8; ++i) { const float lb = lbv[i]; const float sg = sigm(fl[i]);
;             const float f = lb + (1.f - lb) * sg; lf[i] = __logf(f); kf[ii * 8 + i] = (1.f - lb) * (1.f - sg); }
;         *(LAS f32x4*)(LF + t * 128 + d0) = (f32x4){lf[0], lf[1], lf[2], lf[3]}; *(LAS f32x4*)(LF + t * 128 + d0 + 4) = (f32x4){lf[4], lf[5], lf[6], lf[7]};
;     }
; }
; __device__ __forceinline__ void hgrn_cumsum_scan(LAS unsigned char* lds, int tid) {
;     LAS float* LF = (LAS float*)lds;
;     LAS float* PT = (LAS float*)(lds + 32768);
;     BAR_LDS();
;     const int d = tid & 127, pt = tid >> 7;
;     float v[16];
; #pragma unroll
;     for (int t = 0; t < 16; ++t) v[t] = LF[(pt * 16 + t) * 128 + d];
; #pragma unroll
;     for (int t = 1; t < 16; ++t) v[t] += v[t - 1];
;     PT[pt * 128 + d] = v[15];
;     BAR_LDS();
	v_pk_add_f32 v[44:45], v[12:13], 1.0 op_sel_hi:[1,0] neg_lo:[1,0] neg_hi:[1,0]
	v_pk_add_f32 v[48:49], v[14:15], 1.0 op_sel_hi:[1,0] neg_lo:[1,0] neg_hi:[1,0]
	v_fma_f32 v12, v50, v44, v12
	v_add_f32_e32 v16, 1.0, v16
	v_cmp_gt_f32_e32 vcc, s28, v12
	v_rcp_f32_e32 v51, v16
	s_waitcnt lgkmcnt(0)
	v_pk_add_f32 v[52:53], v[8:9], 1.0 op_sel_hi:[1,0] neg_lo:[1,0] neg_hi:[1,0]
	v_cndmask_b32_e64 v16, 0, 32, vcc
	v_ldexp_f32 v12, v12, v16
	v_log_f32_e32 v12, v12
	v_fma_f32 v13, v51, v45, v13
	v_pk_add_f32 v[54:55], v[10:11], 1.0 op_sel_hi:[1,0] neg_lo:[1,0] neg_hi:[1,0]
	v_mul_f32_e32 v16, 0x3f317217, v12
	v_fma_f32 v16, v12, s29, -v16
	v_fmac_f32_e32 v16, 0x3377d1cf, v12
	v_fmac_f32_e32 v16, 0x3f317217, v12
	v_cmp_lt_f32_e64 s[50:51], |v12|, s30
	s_nop 1
	v_cndmask_b32_e64 v12, v12, v16, s[50:51]
	v_cndmask_b32_e32 v16, 0, v190, vcc
	v_cmp_gt_f32_e32 vcc, s28, v13
	v_sub_f32_e32 v12, v12, v16
	s_nop 0
	v_cndmask_b32_e64 v16, 0, 32, vcc
	v_ldexp_f32 v13, v13, v16
	v_log_f32_e32 v13, v13
	s_nop 0
	v_mul_f32_e32 v16, 0x3f317217, v13
	v_fma_f32 v16, v13, s29, -v16
	v_fmac_f32_e32 v16, 0x3377d1cf, v13
	v_fmac_f32_e32 v16, 0x3f317217, v13
	v_cmp_lt_f32_e64 s[50:51], |v13|, s30
	s_nop 1
	v_cndmask_b32_e64 v13, v13, v16, s[50:51]
	v_cndmask_b32_e32 v16, 0, v190, vcc
	v_sub_f32_e32 v13, v13, v16
	v_mul_f32_e32 v16, 0xbfb8aa3b, v18
	v_exp_f32_e32 v16, v16
	s_nop 0
	v_add_f32_e32 v16, 1.0, v16
	v_rcp_f32_e32 v56, v16
	v_mul_f32_e32 v16, 0xbfb8aa3b, v19
	v_exp_f32_e32 v16, v16
	v_fma_f32 v14, v56, v48, v14
	v_cmp_gt_f32_e32 vcc, s28, v14
	v_add_f32_e32 v16, 1.0, v16
	v_rcp_f32_e32 v57, v16
	v_cndmask_b32_e64 v16, 0, 32, vcc
	v_ldexp_f32 v14, v14, v16
	v_log_f32_e32 v14, v14
	v_fmac_f32_e32 v15, v57, v49
	v_mul_f32_e32 v16, 0x3f317217, v14
	v_fma_f32 v16, v14, s29, -v16
	v_fmac_f32_e32 v16, 0x3377d1cf, v14
	v_fmac_f32_e32 v16, 0x3f317217, v14
	v_cmp_lt_f32_e64 s[50:51], |v14|, s30
	s_nop 1
	v_cndmask_b32_e64 v14, v14, v16, s[50:51]
	v_cndmask_b32_e32 v16, 0, v190, vcc
	v_cmp_gt_f32_e32 vcc, s28, v15
	v_sub_f32_e32 v14, v14, v16
	s_nop 0
	v_cndmask_b32_e64 v16, 0, 32, vcc
	v_ldexp_f32 v15, v15, v16
	v_log_f32_e32 v15, v15
	s_nop 0
	v_mul_f32_e32 v16, 0x3f317217, v15
	v_fma_f32 v16, v15, s29, -v16
	v_fmac_f32_e32 v16, 0x3377d1cf, v15
	v_fmac_f32_e32 v16, 0x3f317217, v15
	v_cmp_lt_f32_e64 s[50:51], |v15|, s30
	s_nop 1
	v_cndmask_b32_e64 v15, v15, v16, s[50:51]
	v_cndmask_b32_e32 v16, 0, v190, vcc
	v_sub_f32_e32 v15, v15, v16
	v_mul_f32_e32 v16, 0xbfb8aa3b, v21
	v_exp_f32_e32 v16, v16
	s_nop 0
	v_add_f32_e32 v16, 1.0, v16
	v_rcp_f32_e32 v58, v16
	v_mul_f32_e32 v16, 0xbfb8aa3b, v22
	v_exp_f32_e32 v16, v16
	v_fma_f32 v8, v58, v52, v8
	v_cmp_gt_f32_e32 vcc, s28, v8
	v_add_f32_e32 v16, 1.0, v16
	v_rcp_f32_e32 v59, v16
	v_cndmask_b32_e64 v16, 0, 32, vcc
	v_ldexp_f32 v8, v8, v16
	v_log_f32_e32 v8, v8
	v_fma_f32 v9, v59, v53, v9
	v_mul_f32_e32 v16, 0x3f317217, v8
	v_fma_f32 v16, v8, s29, -v16
	v_fmac_f32_e32 v16, 0x3377d1cf, v8
	v_fmac_f32_e32 v16, 0x3f317217, v8
	v_cmp_lt_f32_e64 s[50:51], |v8|, s30
	s_nop 1
	v_cndmask_b32_e64 v8, v8, v16, s[50:51]
	v_cndmask_b32_e32 v16, 0, v190, vcc
	v_cmp_gt_f32_e32 vcc, s28, v9
	v_sub_f32_e32 v8, v8, v16
	s_nop 0
	v_cndmask_b32_e64 v16, 0, 32, vcc
	v_ldexp_f32 v9, v9, v16
	v_log_f32_e32 v9, v9
	s_nop 0
	v_mul_f32_e32 v16, 0x3f317217, v9
	v_fma_f32 v16, v9, s29, -v16
	v_fmac_f32_e32 v16, 0x3377d1cf, v9
	v_fmac_f32_e32 v16, 0x3f317217, v9
	v_cmp_lt_f32_e64 s[50:51], |v9|, s30
	s_nop 1
	v_cndmask_b32_e64 v9, v9, v16, s[50:51]
	v_cndmask_b32_e32 v16, 0, v190, vcc
	v_sub_f32_e32 v9, v9, v16
	v_mul_f32_e32 v16, 0xbfb8aa3b, v23
	v_exp_f32_e32 v16, v16
	s_nop 0
	v_add_f32_e32 v16, 1.0, v16
	v_rcp_f32_e32 v62, v16
	v_mul_f32_e32 v16, 0xbfb8aa3b, v37
	v_exp_f32_e32 v16, v16
	v_fma_f32 v10, v62, v54, v10
	v_cmp_gt_f32_e32 vcc, s28, v10
	v_add_f32_e32 v16, 1.0, v16
	v_rcp_f32_e32 v63, v16
	v_cndmask_b32_e64 v16, 0, 32, vcc
	v_ldexp_f32 v10, v10, v16
	v_log_f32_e32 v10, v10
	v_fmac_f32_e32 v11, v63, v55
	v_mul_f32_e32 v16, 0x3f317217, v10
	v_fma_f32 v16, v10, s29, -v16
	v_fmac_f32_e32 v16, 0x3377d1cf, v10
	v_fmac_f32_e32 v16, 0x3f317217, v10
	v_cmp_lt_f32_e64 s[50:51], |v10|, s30
	s_nop 1
	v_cndmask_b32_e64 v10, v10, v16, s[50:51]
	v_cndmask_b32_e32 v16, 0, v190, vcc
	v_cmp_gt_f32_e32 vcc, s28, v11
	v_sub_f32_e32 v10, v10, v16
	s_nop 0
	v_cndmask_b32_e64 v16, 0, 32, vcc
	v_ldexp_f32 v11, v11, v16
	v_log_f32_e32 v11, v11
	s_nop 0
	v_mul_f32_e32 v16, 0x3f317217, v11
	v_fma_f32 v16, v11, s29, -v16
	v_fmac_f32_e32 v16, 0x3377d1cf, v11
	v_fmac_f32_e32 v16, 0x3f317217, v11
	v_cmp_lt_f32_e64 s[50:51], |v11|, s30
	s_nop 1
	v_cndmask_b32_e64 v11, v11, v16, s[50:51]
	v_cndmask_b32_e32 v16, 0, v190, vcc
	v_sub_f32_e32 v11, v11, v16
	ds_write_b128 v66, v[12:15] offset:16384
	ds_write_b128 v66, v[8:11] offset:16400
	v_lshl_add_u64 v[8:9], s[10:11], 0, v[32:33]
	v_lshlrev_b64 v[8:9], 13, v[8:9]
	v_lshl_add_u64 v[8:9], s[84:85], 0, v[8:9]
	v_lshl_add_u64 v[8:9], v[8:9], 0, s[6:7]
	v_lshl_add_u64 v[8:9], v[8:9], 0, v[144:145]
	v_add_co_u32_e32 v8, vcc, s26, v8
	s_nop 1
	v_addc_co_u32_e32 v9, vcc, 0, v9, vcc
	global_load_dwordx4 v[12:15], v[8:9], off offset:2048
	global_load_dwordx4 v[16:19], v[8:9], off offset:3072
	v_lshl_add_u64 v[8:9], s[10:11], 0, v[34:35]
	v_lshlrev_b64 v[8:9], 13, v[8:9]
	v_lshl_add_u64 v[8:9], s[84:85], 0, v[8:9]
	v_lshl_add_u64 v[8:9], v[8:9], 0, s[6:7]
	v_lshl_add_u64 v[8:9], v[8:9], 0, v[144:145]
	v_add_co_u32_e32 v20, vcc, s26, v8
	s_nop 1
	v_addc_co_u32_e32 v21, vcc, 0, v9, vcc
	global_load_dwordx4 v[8:11], v[20:21], off offset:2048
	s_nop 0
	global_load_dwordx4 v[20:23], v[20:21], off offset:3072
	s_waitcnt lgkmcnt(0)
	s_barrier
	ds_read2st64_b32 v[60:61], v68 offset1:2
	ds_read2st64_b32 v[80:81], v68 offset0:4 offset1:6
	ds_read2st64_b32 v[82:83], v68 offset0:8 offset1:10
	ds_read2st64_b32 v[84:85], v68 offset0:12 offset1:14
	ds_read2st64_b32 v[94:95], v68 offset0:16 offset1:18
	ds_read2st64_b32 v[98:99], v68 offset0:20 offset1:22
	ds_read2st64_b32 v[102:103], v68 offset0:24 offset1:26
	ds_read2st64_b32 v[104:105], v68 offset0:28 offset1:30
	s_waitcnt lgkmcnt(7)
	v_add_f32_e32 v92, v60, v61
	s_waitcnt lgkmcnt(6)
	v_add_f32_e32 v90, v80, v92
	v_add_f32_e32 v91, v81, v90
	s_waitcnt lgkmcnt(5)
	v_add_f32_e32 v88, v82, v91
	v_add_f32_e32 v89, v83, v88
	s_waitcnt lgkmcnt(4)
	v_add_f32_e32 v86, v84, v89
	v_add_f32_e32 v87, v85, v86
	s_waitcnt lgkmcnt(3)
	v_add_f32_e32 v84, v94, v87
	v_add_f32_e32 v85, v95, v84
	s_waitcnt lgkmcnt(2)
	v_add_f32_e32 v82, v98, v85
	v_add_f32_e32 v83, v99, v82
	s_waitcnt lgkmcnt(1)
	v_add_f32_e32 v80, v102, v83
	v_add_f32_e32 v81, v103, v80
	s_waitcnt lgkmcnt(0)
	v_add_f32_e32 v37, v104, v81
	v_add_f32_e32 v61, v105, v37
	ds_write_b32 v101, v61 offset:32768
	s_waitcnt lgkmcnt(0)
	s_barrier
	v_mov_b32_e32 v94, 0
	s_and_saveexec_b64 s[14:15], s[44:45]
	s_cbranch_execnz .LBB0_446
	s_or_b64 exec, exec, s[14:15]
	v_mov_b32_e32 v95, 0
	s_and_saveexec_b64 s[14:15], s[46:47]
	s_cbranch_execnz .LBB0_447

; #define LAS __attribute__((address_space(3)))
; __device__ __forceinline__ float bflo(unsigned u) { return __uint_as_float(u << 16); }
; __device__ __forceinline__ float bfhi(unsigned u) { return __uint_as_float(u & 0xffff0000u); }
; __device__ __forceinline__ float sigm(float x) { return frcp(1.f + fexp(-x)); }
; __device__ __forceinline__ void hgrn_stepA(const Args& a, int l, LAS unsigned char* lds, int tid, int hh, const HIn& in, float (&kf)[16]) {
;     LAS float* LF = (LAS float*)lds;
;     LAS float* PT = (LAS float*)(lds + 32768);
; #pragma unroll
;     for (int ii = 0; ii < 2; ++ii) {
;         const int cid = tid + 512 * ii, t = cid >> 4, d0 = (cid & 15) * 8;
;         const u32x4 u = in.f[ii];
;         float fl[8] = {bflo(u.x), bfhi(u.x), bflo(u.y), bfhi(u.y), bflo(u.z), bfhi(u.z), bflo(u.w), bfhi(u.w)};
;         float lf[8];
;         const LAS float* LB = (const LAS float*)(lds + 106496) + hh * 128 + d0; const f32x4 lb0 = *(const LAS f32x4*)LB, lb1 = *(const LAS f32x4*)(LB + 4);
;         const float lbv[8] = {lb0.x, lb0.y, lb0.z, lb0.w, lb1.x, lb1.y, lb1.z, lb1.w};
; #pragma unroll
;         for (int i = 0; i < 8; ++i) { const float lb = lbv[i]; const float sg = sigm(fl[i]);
;             const float f = lb + (1.f - lb) * sg; lf[i] = __logf(f); kf[ii * 8 + i] = (1.f - lb) * (1.f - sg); }
;         *(LAS f32x4*)(LF + t * 128 + d0) = (f32x4){lf[0], lf[1], lf[2], lf[3]}; *(LAS f32x4*)(LF + t * 128 + d0 + 4) = (f32x4){lf[4], lf[5], lf[6], lf[7]};
;     }
; }
; __device__ __forceinline__ void hgrn_stage3_unit(const Args& a, int l, LAS unsigned char* lds, int tid, int u, const HIn& in, HIn& nxt, int unext) {
;     const int lane = tid & 63, w = __builtin_amdgcn_readfirstlane(tid >> 6), fr = lane & 15, fq = lane >> 4;
;     const int bh = u >> 5, c = u & 31, b = bh >> 2, hh = bh & 3; const size_t row0 = (size_t)b * SEQ + c * 64;
;     const int tt = w & 3, vh = w >> 2;
;     bf16_t* proj = (bf16_t*)(a.ws + WS_PROJ);
;     LAS float* LF = (LAS float*)lds;
;     LAS unsigned char* QM = lds + 34816;
;     LAS unsigned char* Q0 = QM + 17408;
;     LAS unsigned char* KM = Q0 + 17408;
;     LAS unsigned char* VN = KM + 17408;
;     LAS float* SSQ = (LAS float*)(VN + 18432);
;     float kf[16];
;     hgrn_stepA(a, l, lds, tid, hh, in, kf);
.LBB0_644:
	s_mov_b32 s4, s8
	s_add_i32 s8, s8, s98
	v_lshlrev_b32_e32 v13, 16, v4
	s_cmp_ge_i32 s8, s99
	v_mul_f32_e32 v13, 0xbfb8aa3b, v13
	s_cselect_b64 s[70:71], -1, 0
	s_cmp_lt_i32 s8, s99
	v_exp_f32_e32 v13, v13
	s_cselect_b32 s5, s8, s4
	s_ashr_i32 s60, s4, 5
	s_and_b32 s9, s60, 3
	v_lshl_add_u32 v12, s9, 9, v170
	v_and_b32_e32 v14, 0xffff0000, v4
	v_lshlrev_b32_e32 v15, 16, v5
	v_and_b32_e32 v16, 0xffff0000, v5
	v_lshlrev_b32_e32 v17, 16, v6
	v_and_b32_e32 v18, 0xffff0000, v6
	v_lshlrev_b32_e32 v19, 16, v7
	v_and_b32_e32 v20, 0xffff0000, v7
	ds_read_b128 v[8:11], v12
	ds_read_b128 v[4:7], v12 offset:16
	v_add_f32_e32 v13, 1.0, v13
	v_rcp_f32_e32 v104, v13
	v_mul_f32_e32 v13, 0xbfb8aa3b, v14
	v_exp_f32_e32 v13, v13
	s_waitcnt lgkmcnt(1)
	v_pk_add_f32 v[106:107], v[8:9], 1.0 op_sel_hi:[1,0] neg_lo:[1,0] neg_hi:[1,0]
	v_pk_add_f32 v[110:111], v[10:11], 1.0 op_sel_hi:[1,0] neg_lo:[1,0] neg_hi:[1,0]
	v_fma_f32 v8, v104, v106, v8
	v_add_f32_e32 v13, 1.0, v13
	v_cmp_gt_f32_e32 vcc, s28, v8
	v_rcp_f32_e32 v105, v13
	s_waitcnt lgkmcnt(0)
	v_pk_add_f32 v[114:115], v[4:5], 1.0 op_sel_hi:[1,0] neg_lo:[1,0] neg_hi:[1,0]
	v_cndmask_b32_e64 v13, 0, 32, vcc
	v_ldexp_f32 v8, v8, v13
	v_log_f32_e32 v8, v8
	v_fma_f32 v9, v105, v107, v9
	v_pk_add_f32 v[138:139], v[6:7], 1.0 op_sel_hi:[1,0] neg_lo:[1,0] neg_hi:[1,0]
	v_and_b32_e32 v14, 0xffff0000, v2
	v_mul_f32_e32 v13, 0x3f317217, v8
	v_fma_f32 v13, v8, s29, -v13
	v_fmac_f32_e32 v13, 0x3377d1cf, v8
	v_fmac_f32_e32 v13, 0x3f317217, v8
	v_cmp_lt_f32_e64 s[58:59], |v8|, s30
	v_readfirstlane_b32 s10, v121
	s_and_b32 s14, s4, 31
	v_cndmask_b32_e64 v8, v8, v13, s[58:59]
	v_cndmask_b32_e32 v13, 0, v190, vcc
	v_cmp_gt_f32_e32 vcc, s28, v9
	v_sub_f32_e32 v8, v8, v13
	s_ashr_i32 s40, s4, 7
	v_cndmask_b32_e64 v13, 0, 32, vcc
	v_ldexp_f32 v9, v9, v13
	v_log_f32_e32 v9, v9
	s_bfe_u32 s11, s10, 0x20006
	s_ashr_i32 s61, s60, 31
	s_ashr_i32 s41, s40, 31
	v_mul_f32_e32 v13, 0x3f317217, v9
	v_fma_f32 v13, v9, s29, -v13
	v_fmac_f32_e32 v13, 0x3377d1cf, v9
	v_fmac_f32_e32 v13, 0x3f317217, v9
	v_cmp_lt_f32_e64 s[58:59], |v9|, s30
	s_lshl_b32 s6, s14, 6
	s_ashr_i32 s36, s10, 8
	v_cndmask_b32_e64 v9, v9, v13, s[58:59]
	v_cndmask_b32_e32 v13, 0, v190, vcc
	v_sub_f32_e32 v9, v9, v13
	v_mul_f32_e32 v13, 0xbfb8aa3b, v15
	v_exp_f32_e32 v13, v13
	v_lshlrev_b32_e32 v15, 16, v3
	s_lshl_b32 s4, s11, 4
	s_lshl_b64 s[16:17], s[60:61], 20
	v_add_f32_e32 v13, 1.0, v13
	v_rcp_f32_e32 v108, v13
	v_mul_f32_e32 v13, 0xbfb8aa3b, v16
	v_exp_f32_e32 v13, v13
	v_and_b32_e32 v16, 0xffff0000, v3
	v_fma_f32 v10, v108, v110, v10
	v_cmp_gt_f32_e32 vcc, s28, v10
	v_add_f32_e32 v13, 1.0, v13
	v_rcp_f32_e32 v109, v13
	v_cndmask_b32_e64 v13, 0, 32, vcc
	v_ldexp_f32 v10, v10, v13
	v_log_f32_e32 v10, v10
	v_fmac_f32_e32 v11, v109, v111
	s_add_u32 s15, s88, s16
	s_addc_u32 s16, s89, s17
	v_mul_f32_e32 v13, 0x3f317217, v10
	v_fma_f32 v13, v10, s29, -v13
	v_fmac_f32_e32 v13, 0x3377d1cf, v10
	v_fmac_f32_e32 v13, 0x3f317217, v10
	v_cmp_lt_f32_e64 s[58:59], |v10|, s30
	s_lshl_b32 s14, s14, 15
	s_add_u32 s14, s15, s14
	v_cndmask_b32_e64 v10, v10, v13, s[58:59]
	v_cndmask_b32_e32 v13, 0, v190, vcc
	v_cmp_gt_f32_e32 vcc, s28, v11
	v_sub_f32_e32 v10, v10, v13
	s_addc_u32 s15, s16, 0
	v_cndmask_b32_e64 v13, 0, 32, vcc
	v_ldexp_f32 v11, v11, v13
	v_log_f32_e32 v11, v11
	v_mov_b32_e32 v125, v145
	v_mul_f32_e32 v13, 0x3f317217, v11
	v_fma_f32 v13, v11, s29, -v13
	v_fmac_f32_e32 v13, 0x3377d1cf, v11
	v_fmac_f32_e32 v13, 0x3f317217, v11
	v_cmp_lt_f32_e64 s[58:59], |v11|, s30
	s_nop 1
	v_cndmask_b32_e64 v11, v11, v13, s[58:59]
	v_cndmask_b32_e32 v13, 0, v190, vcc
	v_sub_f32_e32 v11, v11, v13
	v_mul_f32_e32 v13, 0xbfb8aa3b, v17
	v_exp_f32_e32 v13, v13
	s_nop 0
	v_add_f32_e32 v13, 1.0, v13
	v_rcp_f32_e32 v112, v13
	v_mul_f32_e32 v13, 0xbfb8aa3b, v18
	v_exp_f32_e32 v13, v13
	v_fma_f32 v4, v112, v114, v4
	v_cmp_gt_f32_e32 vcc, s28, v4
	v_add_f32_e32 v13, 1.0, v13
	v_rcp_f32_e32 v113, v13
	v_cndmask_b32_e64 v13, 0, 32, vcc
	v_ldexp_f32 v4, v4, v13
	v_log_f32_e32 v4, v4
	v_fma_f32 v5, v113, v115, v5
	v_mul_f32_e32 v13, 0x3f317217, v4
	v_fma_f32 v13, v4, s29, -v13
	v_fmac_f32_e32 v13, 0x3377d1cf, v4
	v_fmac_f32_e32 v13, 0x3f317217, v4
	v_cmp_lt_f32_e64 s[58:59], |v4|, s30
	s_nop 1
	v_cndmask_b32_e64 v4, v4, v13, s[58:59]
	v_cndmask_b32_e32 v13, 0, v190, vcc
	v_cmp_gt_f32_e32 vcc, s28, v5
	v_sub_f32_e32 v4, v4, v13
	s_nop 0
	v_cndmask_b32_e64 v13, 0, 32, vcc
	v_ldexp_f32 v5, v5, v13
	v_log_f32_e32 v5, v5
	s_nop 0
	v_mul_f32_e32 v13, 0x3f317217, v5
	v_fma_f32 v13, v5, s29, -v13
	v_fmac_f32_e32 v13, 0x3377d1cf, v5
	v_fmac_f32_e32 v13, 0x3f317217, v5
	v_cmp_lt_f32_e64 s[58:59], |v5|, s30
	s_nop 1
	v_cndmask_b32_e64 v5, v5, v13, s[58:59]
	v_cndmask_b32_e32 v13, 0, v190, vcc
	v_sub_f32_e32 v5, v5, v13
	v_mul_f32_e32 v13, 0xbfb8aa3b, v19
	v_exp_f32_e32 v13, v13
	s_nop 0
	v_add_f32_e32 v13, 1.0, v13
	v_rcp_f32_e32 v136, v13
	v_mul_f32_e32 v13, 0xbfb8aa3b, v20
	v_exp_f32_e32 v13, v13
	v_fma_f32 v6, v136, v138, v6
	v_cmp_gt_f32_e32 vcc, s28, v6
	v_add_f32_e32 v13, 1.0, v13
	v_rcp_f32_e32 v137, v13
	v_cndmask_b32_e64 v13, 0, 32, vcc
	v_ldexp_f32 v6, v6, v13
	v_log_f32_e32 v6, v6
	v_fmac_f32_e32 v7, v137, v139
	v_mul_f32_e32 v13, 0x3f317217, v6
	v_fma_f32 v13, v6, s29, -v13
	v_fmac_f32_e32 v13, 0x3377d1cf, v6
	v_fmac_f32_e32 v13, 0x3f317217, v6
	v_cmp_lt_f32_e64 s[58:59], |v6|, s30
	s_nop 1
	v_cndmask_b32_e64 v6, v6, v13, s[58:59]
	v_cndmask_b32_e32 v13, 0, v190, vcc
	v_cmp_gt_f32_e32 vcc, s28, v7
	v_sub_f32_e32 v6, v6, v13
	s_nop 0
	v_cndmask_b32_e64 v13, 0, 32, vcc
	v_ldexp_f32 v7, v7, v13
	v_log_f32_e32 v7, v7
	s_nop 0
	v_mul_f32_e32 v13, 0x3f317217, v7
	v_fma_f32 v13, v7, s29, -v13
	v_fmac_f32_e32 v13, 0x3377d1cf, v7
	v_fmac_f32_e32 v13, 0x3f317217, v7
	v_cmp_lt_f32_e64 s[58:59], |v7|, s30
	s_nop 1
	v_cndmask_b32_e64 v7, v7, v13, s[58:59]
	v_cndmask_b32_e32 v13, 0, v190, vcc
	v_sub_f32_e32 v7, v7, v13
	ds_write_b128 v172, v[8:11]
	ds_write_b128 v172, v[4:7] offset:16
	v_lshlrev_b32_e32 v8, 16, v0
	v_mul_f32_e32 v8, 0xbfb8aa3b, v8
	v_exp_f32_e32 v8, v8
	v_and_b32_e32 v9, 0xffff0000, v0
	v_lshlrev_b32_e32 v10, 16, v1
	v_and_b32_e32 v11, 0xffff0000, v1
	v_lshlrev_b32_e32 v13, 16, v2
	ds_read_b128 v[4:7], v12
	ds_read_b128 v[0:3], v12 offset:16
	v_add_f32_e32 v8, 1.0, v8
	v_rcp_f32_e32 v140, v8
	v_mul_f32_e32 v8, 0xbfb8aa3b, v9
	v_exp_f32_e32 v8, v8
	s_waitcnt lgkmcnt(1)
; #define LAS __attribute__((address_space(3)))
; __device__ __forceinline__ float bflo(unsigned u) { return __uint_as_float(u << 16); }
; __device__ __forceinline__ float bfhi(unsigned u) { return __uint_as_float(u & 0xffff0000u); }
; __device__ __forceinline__ float sigm(float x) { return frcp(1.f + fexp(-x)); }
; __device__ __forceinline__ void hgrn_stepA(const Args& a, int l, LAS unsigned char* lds, int tid, int hh, const HIn& in, float (&kf)[16]) {
;     LAS float* LF = (LAS float*)lds;
;     LAS float* PT = (LAS float*)(lds + 32768);
; #pragma unroll
;     for (int ii = 0; ii < 2; ++ii) {
;         const int cid = tid + 512 * ii, t = cid >> 4, d0 = (cid & 15) * 8;
;         const u32x4 u = in.f[ii];
;         float fl[8] = {bflo(u.x), bfhi(u.x), bflo(u.y), bfhi(u.y), bflo(u.z), bfhi(u.z), bflo(u.w), bfhi(u.w)};
;         float lf[8];
;         const LAS float* LB = (const LAS float*)(lds + 106496) + hh * 128 + d0; const f32x4 lb0 = *(const LAS f32x4*)LB, lb1 = *(const LAS f32x4*)(LB + 4);
;         const float lbv[8] = {lb0.x, lb0.y, lb0.z, lb0.w, lb1.x, lb1.y, lb1.z, lb1.w};
; #pragma unroll
;         for (int i = 0; i < 8; ++i) { const float lb = lbv[i]; const float sg = sigm(fl[i]);
;             const float f = lb + (1.f - lb) * sg; lf[i] = __logf(f); kf[ii * 8 + i] = (1.f - lb) * (1.f - sg); }
;         *(LAS f32x4*)(LF + t * 128 + d0) = (f32x4){lf[0], lf[1], lf[2], lf[3]}; *(LAS f32x4*)(LF + t * 128 + d0 + 4) = (f32x4){lf[4], lf[5], lf[6], lf[7]};
;     }
; }
; __device__ __forceinline__ void hgrn_stage3_unit(const Args& a, int l, LAS unsigned char* lds, int tid, int u, const HIn& in, HIn& nxt, int unext) {
;     ...
;     for (int ks = 0; ks < 4; ++ks)
; #pragma unroll
;         for (int v = 0; v < 4; ++v) stf[ks][v] = *(const bf16x8*)(ST + ((vh * 4 + v) * 16 + fr) * 128 + ks * 32 + fq * 8);
	v_pk_add_f32 v[142:143], v[4:5], 1.0 op_sel_hi:[1,0] neg_lo:[1,0] neg_hi:[1,0]
	v_pk_add_f32 v[162:163], v[6:7], 1.0 op_sel_hi:[1,0] neg_lo:[1,0] neg_hi:[1,0]
	v_fma_f32 v4, v140, v142, v4
	v_add_f32_e32 v8, 1.0, v8
	v_cmp_gt_f32_e32 vcc, s28, v4
	v_rcp_f32_e32 v141, v8
	s_waitcnt lgkmcnt(0)
	v_pk_add_f32 v[166:167], v[0:1], 1.0 op_sel_hi:[1,0] neg_lo:[1,0] neg_hi:[1,0]
	v_cndmask_b32_e64 v8, 0, 32, vcc
	v_ldexp_f32 v4, v4, v8
	v_log_f32_e32 v4, v4
	v_fma_f32 v5, v141, v143, v5
	v_pk_add_f32 v[158:159], v[2:3], 1.0 op_sel_hi:[1,0] neg_lo:[1,0] neg_hi:[1,0]
	v_mul_f32_e32 v8, 0x3f317217, v4
	v_fma_f32 v8, v4, s29, -v8
	v_fmac_f32_e32 v8, 0x3377d1cf, v4
	v_fmac_f32_e32 v8, 0x3f317217, v4
	v_cmp_lt_f32_e64 s[58:59], |v4|, s30
	s_nop 1
	v_cndmask_b32_e64 v4, v4, v8, s[58:59]
	v_cndmask_b32_e32 v8, 0, v190, vcc
	v_cmp_gt_f32_e32 vcc, s28, v5
	v_sub_f32_e32 v4, v4, v8
	s_nop 0
	v_cndmask_b32_e64 v8, 0, 32, vcc
	v_ldexp_f32 v5, v5, v8
	v_log_f32_e32 v5, v5
	s_nop 0
	v_mul_f32_e32 v8, 0x3f317217, v5
	v_fma_f32 v8, v5, s29, -v8
	v_fmac_f32_e32 v8, 0x3377d1cf, v5
	v_fmac_f32_e32 v8, 0x3f317217, v5
	v_cmp_lt_f32_e64 s[58:59], |v5|, s30
	s_nop 1
	v_cndmask_b32_e64 v5, v5, v8, s[58:59]
	v_cndmask_b32_e32 v8, 0, v190, vcc
	v_sub_f32_e32 v5, v5, v8
	v_mul_f32_e32 v8, 0xbfb8aa3b, v10
	v_exp_f32_e32 v8, v8
	s_nop 0
	v_add_f32_e32 v8, 1.0, v8
	v_rcp_f32_e32 v160, v8
	v_mul_f32_e32 v8, 0xbfb8aa3b, v11
	v_exp_f32_e32 v8, v8
	v_fma_f32 v6, v160, v162, v6
	v_cmp_gt_f32_e32 vcc, s28, v6
	v_add_f32_e32 v8, 1.0, v8
	v_rcp_f32_e32 v161, v8
	v_cndmask_b32_e64 v8, 0, 32, vcc
	v_ldexp_f32 v6, v6, v8
	v_log_f32_e32 v6, v6
	v_fmac_f32_e32 v7, v161, v163
	v_mul_f32_e32 v8, 0x3f317217, v6
	v_fma_f32 v8, v6, s29, -v8
	v_fmac_f32_e32 v8, 0x3377d1cf, v6
	v_fmac_f32_e32 v8, 0x3f317217, v6
	v_cmp_lt_f32_e64 s[58:59], |v6|, s30
	s_nop 1
	v_cndmask_b32_e64 v6, v6, v8, s[58:59]
	v_cndmask_b32_e32 v8, 0, v190, vcc
	v_cmp_gt_f32_e32 vcc, s28, v7
	v_sub_f32_e32 v6, v6, v8
	s_nop 0
	v_cndmask_b32_e64 v8, 0, 32, vcc
	v_ldexp_f32 v7, v7, v8
	v_log_f32_e32 v7, v7
	s_nop 0
	v_mul_f32_e32 v8, 0x3f317217, v7
	v_fma_f32 v8, v7, s29, -v8
	v_fmac_f32_e32 v8, 0x3377d1cf, v7
	v_fmac_f32_e32 v8, 0x3f317217, v7
	v_cmp_lt_f32_e64 s[58:59], |v7|, s30
	s_nop 1
	v_cndmask_b32_e64 v7, v7, v8, s[58:59]
	v_cndmask_b32_e32 v8, 0, v190, vcc
	v_sub_f32_e32 v7, v7, v8
	v_mul_f32_e32 v8, 0xbfb8aa3b, v13
	v_exp_f32_e32 v8, v8
	s_nop 0
	v_add_f32_e32 v8, 1.0, v8
	v_rcp_f32_e32 v164, v8
	v_mul_f32_e32 v8, 0xbfb8aa3b, v14
	v_exp_f32_e32 v8, v8
	v_fma_f32 v0, v164, v166, v0
	v_cmp_gt_f32_e32 vcc, s28, v0
	v_add_f32_e32 v8, 1.0, v8
	v_rcp_f32_e32 v165, v8
	v_cndmask_b32_e64 v8, 0, 32, vcc
	v_ldexp_f32 v0, v0, v8
	v_log_f32_e32 v0, v0
	v_fma_f32 v1, v165, v167, v1
	v_mul_f32_e32 v8, 0x3f317217, v0
	v_fma_f32 v8, v0, s29, -v8
	v_fmac_f32_e32 v8, 0x3377d1cf, v0
	v_fmac_f32_e32 v8, 0x3f317217, v0
	v_cmp_lt_f32_e64 s[58:59], |v0|, s30
	s_nop 1
	v_cndmask_b32_e64 v0, v0, v8, s[58:59]
	v_cndmask_b32_e32 v8, 0, v190, vcc
	v_cmp_gt_f32_e32 vcc, s28, v1
	v_sub_f32_e32 v0, v0, v8
	s_nop 0
	v_cndmask_b32_e64 v8, 0, 32, vcc
	v_ldexp_f32 v1, v1, v8
	v_log_f32_e32 v1, v1
	s_nop 0
	v_mul_f32_e32 v8, 0x3f317217, v1
	v_fma_f32 v8, v1, s29, -v8
	v_fmac_f32_e32 v8, 0x3377d1cf, v1
	v_fmac_f32_e32 v8, 0x3f317217, v1
	v_cmp_lt_f32_e64 s[58:59], |v1|, s30
	s_nop 1
	v_cndmask_b32_e64 v1, v1, v8, s[58:59]
	v_cndmask_b32_e32 v8, 0, v190, vcc
	v_sub_f32_e32 v1, v1, v8
	v_mul_f32_e32 v8, 0xbfb8aa3b, v15
	v_exp_f32_e32 v8, v8
	s_nop 0
	v_add_f32_e32 v8, 1.0, v8
	v_rcp_f32_e32 v156, v8
	v_mul_f32_e32 v8, 0xbfb8aa3b, v16
	v_exp_f32_e32 v8, v8
	v_fma_f32 v2, v156, v158, v2
	v_cmp_gt_f32_e32 vcc, s28, v2
	v_add_f32_e32 v8, 1.0, v8
	v_rcp_f32_e32 v157, v8
	v_cndmask_b32_e64 v8, 0, 32, vcc
	v_ldexp_f32 v2, v2, v8
	v_log_f32_e32 v2, v2
	v_fmac_f32_e32 v3, v157, v159
	v_mul_f32_e32 v8, 0x3f317217, v2
	v_fma_f32 v8, v2, s29, -v8
	v_fmac_f32_e32 v8, 0x3377d1cf, v2
	v_fmac_f32_e32 v8, 0x3f317217, v2
	v_cmp_lt_f32_e64 s[58:59], |v2|, s30
	s_nop 1
	v_cndmask_b32_e64 v2, v2, v8, s[58:59]
	v_cndmask_b32_e32 v8, 0, v190, vcc
	v_cmp_gt_f32_e32 vcc, s28, v3
	v_sub_f32_e32 v2, v2, v8
	s_nop 0
	v_cndmask_b32_e64 v8, 0, 32, vcc
	v_ldexp_f32 v3, v3, v8
	v_log_f32_e32 v3, v3
	s_nop 0
	v_mul_f32_e32 v8, 0x3f317217, v3
	v_fma_f32 v8, v3, s29, -v8
	v_fmac_f32_e32 v8, 0x3377d1cf, v3
	v_fmac_f32_e32 v8, 0x3f317217, v3
	v_cmp_lt_f32_e64 s[58:59], |v3|, s30
	s_nop 1
	v_cndmask_b32_e64 v3, v3, v8, s[58:59]
	v_cndmask_b32_e32 v8, 0, v190, vcc
	v_sub_f32_e32 v3, v3, v8
	ds_write_b128 v172, v[4:7] offset:16384
	ds_write_b128 v172, v[0:3] offset:16400
	v_lshlrev_b32_e32 v14, 3, v120
	s_mov_b64 s[16:17], 0x400
	s_mov_b64 s[18:19], 0x800
	v_lshl_or_b32 v2, s36, 13, v14
	v_or_b32_e32 v6, 0x800, v2
	v_ashrrev_i32_e32 v7, 31, v6
	v_lshl_add_u64 v[0:1], v[144:145], 4, s[14:15]
	v_lshlrev_b64 v[6:7], 1, v[6:7]
	v_lshl_add_u64 v[8:9], v[0:1], 0, v[6:7]
	v_ashrrev_i32_e32 v3, 31, v2
	global_load_dwordx4 v[60:63], v[8:9], off
; #define LAS __attribute__((address_space(3)))
; #define BAR_LDS() do { asm volatile("s_waitcnt lgkmcnt(0)" ::: "memory"); __builtin_amdgcn_s_barrier(); asm volatile("" ::: "memory"); } while (0)
; __device__ __forceinline__ void hgrn_cumsum_scan(LAS unsigned char* lds, int tid) {
;     LAS float* LF = (LAS float*)lds;
;     LAS float* PT = (LAS float*)(lds + 32768);
;     BAR_LDS();
;     const int d = tid & 127, pt = tid >> 7;
;     float v[16];
; #pragma unroll
;     for (int t = 0; t < 16; ++t) v[t] = LF[(pt * 16 + t) * 128 + d];
; #pragma unroll
;     for (int t = 1; t < 16; ++t) v[t] += v[t - 1];
;     PT[pt * 128 + d] = v[15];
;     BAR_LDS();
; __device__ __forceinline__ void hgrn_stage3_unit(const Args& a, int l, LAS unsigned char* lds, int tid, int u, const HIn& in, HIn& nxt, int unext) {
;     ...
;     const size_t row = row0 + tt * 16 + fr;
;     const bf16_t* ST = (const bf16_t*)(a.ws + WS_H) + ((size_t)bh * 32 + c) * 16384;
;     bf16x8 stf[4][4]; u32x2 zz[4];
; #pragma unroll
;     for (int ks = 0; ks < 4; ++ks)
; #pragma unroll
;         for (int v = 0; v < 4; ++v) stf[ks][v] = *(const bf16x8*)(ST + ((vh * 4 + v) * 16 + fr) * 128 + ks * 32 + fq * 8);
; #pragma unroll
;     for (int v = 0; v < 4; ++v) zz[v] = *(const u32x2*)(proj + row * NCOL + CZ + 512 + hh * 128 + (vh * 4 + v) * 16 + fq * 4);
;     hgrn_load<true>(a, tid, unext, nxt);
;     hgrn_cumsum_scan(lds, tid);
	v_or_b32_e32 v8, 0x1000, v2
	v_lshl_add_u64 v[4:5], v[2:3], 1, v[0:1]
	v_ashrrev_i32_e32 v9, 31, v8
	v_or_b32_e32 v2, 0x1800, v2
	v_lshlrev_b64 v[8:9], 1, v[8:9]
	v_ashrrev_i32_e32 v3, 31, v2
	v_lshl_add_u64 v[10:11], v[0:1], 0, v[8:9]
	v_lshlrev_b64 v[2:3], 1, v[2:3]
	global_load_dwordx4 v[92:95], v[10:11], off
	v_lshl_add_u64 v[10:11], v[0:1], 0, v[2:3]
	global_load_dwordx4 v[96:99], v[10:11], off
	v_lshl_add_u64 v[10:11], v[0:1], 0, s[16:17]
	v_lshl_add_u64 v[12:13], v[10:11], 0, v[6:7]
	global_load_dwordx4 v[40:43], v[12:13], off
	v_lshl_add_u64 v[12:13], v[10:11], 0, v[8:9]
	v_lshl_add_u64 v[10:11], v[10:11], 0, v[2:3]
	global_load_dwordx4 v[44:47], v[12:13], off
	global_load_dwordx4 v[52:55], v[10:11], off
	v_lshl_add_u64 v[10:11], v[0:1], 0, s[18:19]
	s_mov_b64 s[14:15], 0xc00
	v_lshl_add_u64 v[12:13], v[10:11], 0, v[6:7]
	v_lshl_add_u64 v[0:1], v[0:1], 0, s[14:15]
	s_lshl_b64 s[14:15], s[40:41], 11
	global_load_dwordx4 v[36:39], v[4:5], off
	global_load_dwordx4 v[32:35], v[4:5], off offset:1024
	global_load_dwordx4 v[56:59], v[4:5], off offset:2048
	global_load_dwordx4 v[48:51], v[4:5], off offset:3072
	global_load_dwordx4 v[76:79], v[12:13], off
	v_lshl_add_u64 v[12:13], v[10:11], 0, v[8:9]
	v_lshl_add_u64 v[10:11], v[10:11], 0, v[2:3]
	v_lshl_add_u64 v[4:5], v[0:1], 0, v[6:7]
	s_or_b32 s6, s14, s6
	global_load_dwordx4 v[88:91], v[10:11], off
	global_load_dwordx4 v[64:67], v[4:5], off
	v_lshl_add_u64 v[4:5], v[0:1], 0, v[8:9]
	v_lshl_add_u64 v[0:1], v[0:1], 0, v[2:3]
	s_or_b32 s6, s6, s4
	global_load_dwordx4 v[68:71], v[4:5], off
	global_load_dwordx4 v[80:83], v[0:1], off
	v_mov_b32_e32 v1, s15
	v_or_b32_e32 v0, s6, v120
	v_lshlrev_b64 v[0:1], 13, v[0:1]
	v_lshl_add_u64 v[134:135], s[84:85], 0, v[0:1]
	s_lshl_b32 s6, s9, 8
	v_lshl_add_u64 v[0:1], v[134:135], 0, s[6:7]
	s_lshl_b32 s40, s36, 6
	v_lshlrev_b32_e32 v2, 1, v122
	v_mov_b32_e32 v3, v145
	v_lshl_add_u64 v[0:1], v[0:1], 0, v[2:3]
	s_ashr_i32 s41, s40, 31
	s_ashr_i32 s14, s5, 7
	v_lshl_add_u64 v[0:1], s[40:41], 1, v[0:1]
	s_ashr_i32 s15, s14, 31
	s_lshl_b32 s6, s5, 6
	v_lshl_add_u64 v[2:3], v[0:1], 0, s[12:13]
	v_add_co_u32_e32 v0, vcc, s26, v0
	s_lshl_b64 s[14:15], s[14:15], 11
	s_and_b32 s6, s6, 0x7c0
	v_addc_co_u32_e32 v1, vcc, 0, v1, vcc
	s_or_b32 s14, s14, s6
	global_load_dwordx4 v[84:87], v[12:13], off
	global_load_dwordx2 v[132:133], v[0:1], off
	global_load_dwordx2 v[130:131], v[2:3], off offset:32
	global_load_dwordx2 v[128:129], v[2:3], off offset:64
	global_load_dwordx2 v[126:127], v[2:3], off offset:96
	v_lshl_add_u64 v[0:1], s[14:15], 0, v[116:117]
	v_lshlrev_b64 v[0:1], 13, v[0:1]
	s_lshl_b32 s5, s5, 3
	v_lshl_add_u64 v[0:1], s[84:85], 0, v[0:1]
	s_and_b32 s6, s5, 0x300
	v_lshl_add_u64 v[0:1], v[0:1], 0, s[6:7]
	v_lshl_add_u64 v[0:1], v[0:1], 0, v[124:125]
	v_add_co_u32_e32 v2, vcc, s26, v0
	s_nop 1
	v_addc_co_u32_e32 v3, vcc, 0, v1, vcc
	global_load_dwordx4 v[4:7], v[2:3], off offset:2048
	global_load_dwordx4 v[8:11], v[2:3], off offset:3072
	global_load_dwordx4 v[12:15], v[0:1], off offset:1024
	v_lshl_add_u64 v[0:1], s[14:15], 0, v[118:119]
	v_lshlrev_b64 v[0:1], 13, v[0:1]
	v_lshl_add_u64 v[0:1], s[84:85], 0, v[0:1]
	v_lshl_add_u64 v[0:1], v[0:1], 0, s[6:7]
	v_lshl_add_u64 v[20:21], v[0:1], 0, v[124:125]
	v_add_co_u32_e32 v16, vcc, s26, v20
	s_nop 1
	v_addc_co_u32_e32 v17, vcc, 0, v21, vcc
	global_load_dwordx4 v[0:3], v[16:17], off offset:2048
	s_nop 0
	global_load_dwordx4 v[16:19], v[16:17], off offset:3072
	s_nop 0
	global_load_dwordx4 v[20:23], v[20:21], off offset:1024
	s_waitcnt lgkmcnt(0)
	s_barrier
	ds_read2st64_b32 v[168:169], v175 offset1:2
	ds_read2st64_b32 v[206:207], v175 offset0:4 offset1:6
	ds_read2st64_b32 v[208:209], v175 offset0:8 offset1:10
	ds_read2st64_b32 v[218:219], v175 offset0:12 offset1:14
	ds_read2st64_b32 v[220:221], v175 offset0:16 offset1:18
	ds_read2st64_b32 v[222:223], v175 offset0:20 offset1:22
	ds_read2st64_b32 v[224:225], v175 offset0:24 offset1:26
	ds_read2st64_b32 v[226:227], v175 offset0:28 offset1:30
	s_waitcnt lgkmcnt(7)
	v_add_f32_e32 v217, v168, v169
	s_waitcnt lgkmcnt(6)
	v_add_f32_e32 v215, v206, v217
	v_add_f32_e32 v216, v207, v215
	s_waitcnt lgkmcnt(5)
	v_add_f32_e32 v213, v208, v216
	v_add_f32_e32 v214, v209, v213
	s_waitcnt lgkmcnt(4)
	v_add_f32_e32 v211, v218, v214
	v_add_f32_e32 v212, v219, v211
	s_waitcnt lgkmcnt(3)
	v_add_f32_e32 v209, v220, v212
	v_add_f32_e32 v210, v221, v209
	s_waitcnt lgkmcnt(2)
	v_add_f32_e32 v207, v222, v210
	v_add_f32_e32 v208, v223, v207
	s_waitcnt lgkmcnt(1)
	v_add_f32_e32 v205, v224, v208
	v_add_f32_e32 v206, v225, v205
	s_waitcnt lgkmcnt(0)
	v_add_f32_e32 v125, v226, v206
	v_add_f32_e32 v169, v227, v125
	ds_write_b32 v123, v169 offset:32768
	s_waitcnt lgkmcnt(0)
	s_barrier
	v_mov_b32_e32 v218, 0
	v_mov_b32_e32 v219, 0
	s_and_saveexec_b64 s[14:15], s[42:43]
	s_cbranch_execnz .LBB0_654
	s_or_b64 exec, exec, s[14:15]
	v_mov_b32_e32 v220, 0
	s_and_saveexec_b64 s[14:15], s[44:45]
	s_cbranch_execnz .LBB0_655
